# v24 + GEMM K-loop priority polarity swapped: load segments run at prio 1, MFMA blocks at prio 0 (the loading half is the interval pole)
# baseline (speedup 1.0000x reference)
; #define PG8_STAGE(bufoff, gbase, voff) do { _Pragma("unroll") for (int _i = 0; _i < 2; ++_i) \
;         __builtin_amdgcn_global_load_lds((const unsigned*)((const char*)(gbase) + (voff)[_i]), (PG8_LAS unsigned*)(lds + (bufoff) + ldsw + _i * 8192), 16, 0, 0); } while (0)
; #define PG8_LDA(dst, b, h) do { _Pragma("unroll") for (int m = 0; m < 4; ++m) _Pragma("unroll") for (int k = 0; k < 2; ++k) dst[m][k] = *(const PG8_LAS bf16x8*)(lds + PG8_SA(b, h) + aoff + m * 2048 + k * 1024); } while (0)
; #define PG8_LDB(dst, b, h) do { _Pragma("unroll") for (int n = 0; n < 2; ++n) _Pragma("unroll") for (int k = 0; k < 2; ++k) dst[n][k] = *(const PG8_LAS bf16x8*)(lds + PG8_SB(b, h) + boff + n * 2048 + k * 1024); } while (0)
; #define PG8_MMA(ai, bj, At, Bt) do { __builtin_amdgcn_s_setprio(1); _Pragma("unroll") for (int m = 0; m < 4; ++m) _Pragma("unroll") for (int n = 0; n < 2; ++n) _Pragma("unroll") for (int k = 0; k < 2; ++k) \
;         acc[ai][bj][m][n] = __builtin_amdgcn_mfma_f32_16x16x32_bf16(Bt[n][k], At[m][k], acc[ai][bj][m][n], 0, 0, 0); __builtin_amdgcn_s_setprio(0); } while (0)
; #define PG8_WAIT_V(n) asm volatile("s_waitcnt vmcnt(" #n ")" ::: "memory")
; #define PG8_WAIT_L(n) asm volatile("s_waitcnt lgkmcnt(" #n ")" ::: "memory")
; #define PG8_BAR __builtin_amdgcn_s_barrier()
; #define PG8_SCHED __builtin_amdgcn_sched_barrier(0)
; template <class Epi, class Sched, bool ALIGN_EPI = false, bool SP2 = false>
; __device__ __forceinline__ void gemm_phase(PG8_LAS unsigned char* lds, const Gemm g, const Sched& S, const Epi& E) {
;     ...
;             if constexpr (SP2) {
;             PG8_LDB(B0, 0, 0); PG8_LDB(B1, 0, 1); PG8_SCHED; PG8_LDA(At, 0, 0); PG8_STAGE(PG8_SA(1, 1), a1 + hstep, voffA);
;             PG8_WAIT_V(8); PG8_WAIT_L(0); PG8_BAR; PG8_MMA(0, 0, At, B0); PG8_MMA(0, 1, At, B1); PG8_BAR; PG8_SCHED;
;             PG8_LDA(At, 0, 1); PG8_STAGE(PG8_SB(0, 0), b2, voffB); PG8_STAGE(PG8_SB(0, 1), b2 + hstep, voffB); PG8_STAGE(PG8_SA(0, 0), a2, voffA);
.LBB0_687:
	s_add_u32 s8, s8, 0x80
	s_addc_u32 s9, s9, 0
	s_add_u32 s27, s16, 0x100
	s_addc_u32 s30, s17, 0
	s_mov_b32 s16, 0
	s_waitcnt lgkmcnt(0)
	s_waitcnt lgkmcnt(0)
	s_add_i32 s31, s16, 2
	s_add_u32 s36, s8, 0x80
	s_addc_u32 s17, s9, 0
	s_add_i32 s41, 0, 0x10000
	s_cmp_eq_u32 s72, s16
	s_cselect_b32 s17, s1, s17
	s_cselect_b32 s16, s0, s36
	s_cselect_b32 vcc_hi, s93, s30
	s_cselect_b32 vcc_lo, s92, s27
	s_add_i32 s36, 0, 0x14000
	v_add_u32_e32 v152, s41, v161
	v_add_u32_e32 v178, s36, v161
	ds_read_b128 v[140:143], v152
	ds_read_b128 v[144:147], v152 offset:1024
	ds_read_b128 v[148:151], v152 offset:2048
	ds_read_b128 v[152:155], v152 offset:3072
	ds_read_b128 v[156:159], v178
	ds_read_b128 v[170:173], v178 offset:1024
	ds_read_b128 v[174:177], v178 offset:2048
	ds_read_b128 v[178:181], v178 offset:3072
	v_lshl_add_u64 v[210:211], s[8:9], 0, v[136:137]
	s_add_i32 m0, s76, 0xc000
	ds_read_b128 v[182:185], v169
	ds_read_b128 v[186:189], v169 offset:1024
	ds_read_b128 v[190:193], v169 offset:2048
	ds_read_b128 v[194:197], v169 offset:3072
	ds_read_b128 v[198:201], v169 offset:4096
	ds_read_b128 v[202:205], v169 offset:5120
	ds_read_b128 v[206:209], v169 offset:6144
	ds_read_b128 v[230:233], v169 offset:7168
	global_load_lds_dwordx4 v[210:211], off
	v_lshl_add_u64 v[210:211], s[8:9], 0, v[138:139]
	s_add_i32 m0, s76, 0xe000
	s_nop 0
	global_load_lds_dwordx4 v[210:211], off
	s_waitcnt vmcnt(8)
	s_waitcnt lgkmcnt(0)
	s_barrier
	s_setprio 0
	s_waitcnt lgkmcnt(0)
	v_mfma_f32_16x16x32_bf16 v[126:129], v[140:143], v[182:185], 0
	v_mfma_f32_16x16x32_bf16 v[122:125], v[148:151], v[182:185], 0
	v_mfma_f32_16x16x32_bf16 v[110:113], v[140:143], v[190:193], 0
	v_mfma_f32_16x16x32_bf16 v[106:109], v[148:151], v[190:193], 0
	v_mfma_f32_16x16x32_bf16 v[94:97], v[140:143], v[198:201], 0
	v_mfma_f32_16x16x32_bf16 v[90:93], v[148:151], v[198:201], 0
	v_mfma_f32_16x16x32_bf16 v[78:81], v[140:143], v[206:209], 0
	v_mfma_f32_16x16x32_bf16 v[74:77], v[148:151], v[206:209], 0
	v_mfma_f32_16x16x32_bf16 v[126:129], v[144:147], v[186:189], v[126:129]
	v_mfma_f32_16x16x32_bf16 v[122:125], v[152:155], v[186:189], v[122:125]
	v_mfma_f32_16x16x32_bf16 v[110:113], v[144:147], v[194:197], v[110:113]
	v_mfma_f32_16x16x32_bf16 v[106:109], v[152:155], v[194:197], v[106:109]
	v_mfma_f32_16x16x32_bf16 v[94:97], v[144:147], v[202:205], v[94:97]
	v_mfma_f32_16x16x32_bf16 v[90:93], v[152:155], v[202:205], v[90:93]
	v_mfma_f32_16x16x32_bf16 v[78:81], v[144:147], v[230:233], v[78:81]
	v_mfma_f32_16x16x32_bf16 v[74:77], v[152:155], v[230:233], v[74:77]
	s_setprio 1
	s_setprio 0
	v_mfma_f32_16x16x32_bf16 v[118:121], v[156:159], v[182:185], 0
	v_mfma_f32_16x16x32_bf16 v[114:117], v[174:177], v[182:185], 0
	v_mfma_f32_16x16x32_bf16 v[102:105], v[156:159], v[190:193], 0
	v_mfma_f32_16x16x32_bf16 v[98:101], v[174:177], v[190:193], 0
	v_mfma_f32_16x16x32_bf16 v[86:89], v[156:159], v[198:201], 0
	v_mfma_f32_16x16x32_bf16 v[82:85], v[174:177], v[198:201], 0
	v_mfma_f32_16x16x32_bf16 v[70:73], v[156:159], v[206:209], 0
	v_mfma_f32_16x16x32_bf16 v[66:69], v[174:177], v[206:209], 0
	v_mfma_f32_16x16x32_bf16 v[118:121], v[170:173], v[186:189], v[118:121]
	v_mfma_f32_16x16x32_bf16 v[114:117], v[178:181], v[186:189], v[114:117]
	v_mfma_f32_16x16x32_bf16 v[102:105], v[170:173], v[194:197], v[102:105]
	v_mfma_f32_16x16x32_bf16 v[98:101], v[178:181], v[194:197], v[98:101]
	v_mfma_f32_16x16x32_bf16 v[86:89], v[170:173], v[202:205], v[86:89]
	v_mfma_f32_16x16x32_bf16 v[82:85], v[178:181], v[202:205], v[82:85]
	v_mfma_f32_16x16x32_bf16 v[70:73], v[170:173], v[230:233], v[70:73]
	v_mfma_f32_16x16x32_bf16 v[66:69], v[178:181], v[230:233], v[66:69]
	s_setprio 1
	s_barrier
	s_add_i32 s41, s41, s65
	v_lshl_add_u64 v[210:211], vcc, 0, v[64:65]
	s_mov_b32 m0, s41
	ds_read_b128 v[182:185], v169 offset:16384
	ds_read_b128 v[186:189], v169 offset:17408
	ds_read_b128 v[190:193], v169 offset:18432
	ds_read_b128 v[194:197], v169 offset:19456
	ds_read_b128 v[198:201], v169 offset:20480
	ds_read_b128 v[202:205], v169 offset:21504
	ds_read_b128 v[206:209], v169 offset:22528
	ds_read_b128 v[230:233], v169 offset:23552
	global_load_lds_dwordx4 v[210:211], off
	s_add_i32 m0, s41, 0x2000
	v_lshl_add_u64 v[234:235], vcc, 0, v[134:135]
	s_add_u32 vcc_lo, vcc_lo, s4
	s_addc_u32 vcc_hi, vcc_hi, 0
	s_add_i32 s36, s36, s65
	global_load_lds_dwordx4 v[234:235], off
	v_lshl_add_u64 v[236:237], vcc, 0, v[64:65]
	s_mov_b32 m0, s36
	v_lshl_add_u64 v[238:239], vcc, 0, v[134:135]
	global_load_lds_dwordx4 v[236:237], off
	s_add_i32 m0, s36, 0x2000
	v_lshl_add_u64 v[244:245], s[16:17], 0, v[130:131]
	global_load_lds_dwordx4 v[238:239], off
	s_mov_b32 m0, s76
	v_lshl_add_u64 v[246:247], s[16:17], 0, v[132:133]
	global_load_lds_dwordx4 v[244:245], off
	s_mov_b32 m0, s2
	s_nop 0
	global_load_lds_dwordx4 v[246:247], off
	s_waitcnt vmcnt(8)
	s_waitcnt lgkmcnt(0)
	s_barrier
; #define PG8_STAGE(bufoff, gbase, voff) do { _Pragma("unroll") for (int _i = 0; _i < 2; ++_i) \
;         __builtin_amdgcn_global_load_lds((const unsigned*)((const char*)(gbase) + (voff)[_i]), (PG8_LAS unsigned*)(lds + (bufoff) + ldsw + _i * 8192), 16, 0, 0); } while (0)
; #define PG8_LDA(dst, b, h) do { _Pragma("unroll") for (int m = 0; m < 4; ++m) _Pragma("unroll") for (int k = 0; k < 2; ++k) dst[m][k] = *(const PG8_LAS bf16x8*)(lds + PG8_SA(b, h) + aoff + m * 2048 + k * 1024); } while (0)
; #define PG8_LDB(dst, b, h) do { _Pragma("unroll") for (int n = 0; n < 2; ++n) _Pragma("unroll") for (int k = 0; k < 2; ++k) dst[n][k] = *(const PG8_LAS bf16x8*)(lds + PG8_SB(b, h) + boff + n * 2048 + k * 1024); } while (0)
; #define PG8_MMA(ai, bj, At, Bt) do { __builtin_amdgcn_s_setprio(1); _Pragma("unroll") for (int m = 0; m < 4; ++m) _Pragma("unroll") for (int n = 0; n < 2; ++n) _Pragma("unroll") for (int k = 0; k < 2; ++k) \
;         acc[ai][bj][m][n] = __builtin_amdgcn_mfma_f32_16x16x32_bf16(Bt[n][k], At[m][k], acc[ai][bj][m][n], 0, 0, 0); __builtin_amdgcn_s_setprio(0); } while (0)
; #define PG8_WAIT_V(n) asm volatile("s_waitcnt vmcnt(" #n ")" ::: "memory")
; #define PG8_WAIT_L(n) asm volatile("s_waitcnt lgkmcnt(" #n ")" ::: "memory")
; #define PG8_BAR __builtin_amdgcn_s_barrier()
; #define PG8_SCHED __builtin_amdgcn_sched_barrier(0)
; template <class Epi, class Sched, bool ALIGN_EPI = false, bool SP2 = false>
; __device__ __forceinline__ void gemm_phase(PG8_LAS unsigned char* lds, const Gemm g, const Sched& S, const Epi& E) {
;     ...
;             PG8_WAIT_V(8); PG8_WAIT_L(0); PG8_BAR; PG8_MMA(1, 0, At, B0); PG8_MMA(1, 1, At, B1); PG8_BAR; PG8_SCHED;
;             PG8_LDB(B0, 1, 0); PG8_LDB(B1, 1, 1); PG8_SCHED; PG8_LDA(At, 1, 0); PG8_STAGE(PG8_SA(0, 1), a2 + hstep, voffA);
;             PG8_WAIT_V(8); PG8_WAIT_L(0); PG8_BAR; PG8_MMA(0, 0, At, B0); PG8_MMA(0, 1, At, B1); PG8_BAR; PG8_SCHED;
	s_setprio 0
	s_waitcnt lgkmcnt(0)
	v_mfma_f32_16x16x32_bf16 v[60:63], v[140:143], v[182:185], 0
	v_mfma_f32_16x16x32_bf16 v[56:59], v[148:151], v[182:185], 0
	v_mfma_f32_16x16x32_bf16 v[44:47], v[140:143], v[190:193], 0
	v_mfma_f32_16x16x32_bf16 v[40:43], v[148:151], v[190:193], 0
	v_mfma_f32_16x16x32_bf16 v[28:31], v[140:143], v[198:201], 0
	v_mfma_f32_16x16x32_bf16 v[24:27], v[148:151], v[198:201], 0
	v_mfma_f32_16x16x32_bf16 v[12:15], v[140:143], v[206:209], 0
	v_mfma_f32_16x16x32_bf16 v[8:11], v[148:151], v[206:209], 0
	v_mfma_f32_16x16x32_bf16 v[60:63], v[144:147], v[186:189], v[60:63]
	v_mfma_f32_16x16x32_bf16 v[56:59], v[152:155], v[186:189], v[56:59]
	v_mfma_f32_16x16x32_bf16 v[44:47], v[144:147], v[194:197], v[44:47]
	v_mfma_f32_16x16x32_bf16 v[40:43], v[152:155], v[194:197], v[40:43]
	v_mfma_f32_16x16x32_bf16 v[28:31], v[144:147], v[202:205], v[28:31]
	v_mfma_f32_16x16x32_bf16 v[24:27], v[152:155], v[202:205], v[24:27]
	v_mfma_f32_16x16x32_bf16 v[12:15], v[144:147], v[230:233], v[12:15]
	v_mfma_f32_16x16x32_bf16 v[8:11], v[152:155], v[230:233], v[8:11]
	s_setprio 1
	s_setprio 0
	v_mfma_f32_16x16x32_bf16 v[52:55], v[156:159], v[182:185], 0
	v_mfma_f32_16x16x32_bf16 v[48:51], v[174:177], v[182:185], 0
	v_mfma_f32_16x16x32_bf16 v[36:39], v[156:159], v[190:193], 0
	v_mfma_f32_16x16x32_bf16 v[32:35], v[174:177], v[190:193], 0
	v_mfma_f32_16x16x32_bf16 v[20:23], v[156:159], v[198:201], 0
	v_mfma_f32_16x16x32_bf16 v[16:19], v[174:177], v[198:201], 0
	v_mfma_f32_16x16x32_bf16 v[4:7], v[156:159], v[206:209], 0
	v_mfma_f32_16x16x32_bf16 v[0:3], v[174:177], v[206:209], 0
	v_mfma_f32_16x16x32_bf16 v[52:55], v[170:173], v[186:189], v[52:55]
	v_mfma_f32_16x16x32_bf16 v[48:51], v[178:181], v[186:189], v[48:51]
	v_mfma_f32_16x16x32_bf16 v[36:39], v[170:173], v[194:197], v[36:39]
	v_mfma_f32_16x16x32_bf16 v[32:35], v[178:181], v[194:197], v[32:35]
	v_mfma_f32_16x16x32_bf16 v[20:23], v[170:173], v[202:205], v[20:23]
	v_mfma_f32_16x16x32_bf16 v[16:19], v[178:181], v[202:205], v[16:19]
	v_mfma_f32_16x16x32_bf16 v[4:7], v[170:173], v[230:233], v[4:7]
	v_mfma_f32_16x16x32_bf16 v[0:3], v[178:181], v[230:233], v[0:3]
	s_setprio 1
	s_barrier
	s_add_i32 s36, 0, 0x18000
	s_add_i32 s41, 0, 0x1c000
	v_add_u32_e32 v152, s36, v161
	v_add_u32_e32 v178, s41, v161
	ds_read_b128 v[140:143], v152
	ds_read_b128 v[144:147], v152 offset:1024
	ds_read_b128 v[148:151], v152 offset:2048
	ds_read_b128 v[152:155], v152 offset:3072
	ds_read_b128 v[156:159], v178
	ds_read_b128 v[170:173], v178 offset:1024
	ds_read_b128 v[174:177], v178 offset:2048
	ds_read_b128 v[178:181], v178 offset:3072
	s_add_u32 s16, s16, s4
	s_addc_u32 s17, s17, 0
	s_mov_b32 m0, s3
	v_lshl_add_u64 v[248:249], s[16:17], 0, v[130:131]
	ds_read_b128 v[182:185], v169 offset:32768
	ds_read_b128 v[186:189], v169 offset:33792
	ds_read_b128 v[190:193], v169 offset:34816
	ds_read_b128 v[194:197], v169 offset:35840
	ds_read_b128 v[198:201], v169 offset:36864
	ds_read_b128 v[202:205], v169 offset:37888
	ds_read_b128 v[206:209], v169 offset:38912
	ds_read_b128 v[230:233], v169 offset:39936
	global_load_lds_dwordx4 v[248:249], off
	v_lshl_add_u64 v[248:249], s[16:17], 0, v[132:133]
	s_mov_b32 m0, s70
	s_nop 0
	global_load_lds_dwordx4 v[248:249], off
	s_waitcnt vmcnt(8)
	s_waitcnt lgkmcnt(0)
	s_barrier
	s_setprio 0
	s_waitcnt lgkmcnt(0)
	v_mfma_f32_16x16x32_bf16 v[126:129], v[140:143], v[182:185], v[126:129]
	v_mfma_f32_16x16x32_bf16 v[122:125], v[148:151], v[182:185], v[122:125]
	v_mfma_f32_16x16x32_bf16 v[110:113], v[140:143], v[190:193], v[110:113]
	v_mfma_f32_16x16x32_bf16 v[106:109], v[148:151], v[190:193], v[106:109]
	v_mfma_f32_16x16x32_bf16 v[94:97], v[140:143], v[198:201], v[94:97]
	v_mfma_f32_16x16x32_bf16 v[90:93], v[148:151], v[198:201], v[90:93]
	v_mfma_f32_16x16x32_bf16 v[78:81], v[140:143], v[206:209], v[78:81]
	v_mfma_f32_16x16x32_bf16 v[74:77], v[148:151], v[206:209], v[74:77]
	v_mfma_f32_16x16x32_bf16 v[126:129], v[144:147], v[186:189], v[126:129]
	v_mfma_f32_16x16x32_bf16 v[122:125], v[152:155], v[186:189], v[122:125]
	v_mfma_f32_16x16x32_bf16 v[110:113], v[144:147], v[194:197], v[110:113]
	v_mfma_f32_16x16x32_bf16 v[106:109], v[152:155], v[194:197], v[106:109]
	v_mfma_f32_16x16x32_bf16 v[94:97], v[144:147], v[202:205], v[94:97]
	v_mfma_f32_16x16x32_bf16 v[90:93], v[152:155], v[202:205], v[90:93]
	v_mfma_f32_16x16x32_bf16 v[78:81], v[144:147], v[230:233], v[78:81]
	v_mfma_f32_16x16x32_bf16 v[74:77], v[152:155], v[230:233], v[74:77]
	s_setprio 1
	s_setprio 0
	v_mfma_f32_16x16x32_bf16 v[118:121], v[156:159], v[182:185], v[118:121]
	v_mfma_f32_16x16x32_bf16 v[114:117], v[174:177], v[182:185], v[114:117]
	v_mfma_f32_16x16x32_bf16 v[102:105], v[156:159], v[190:193], v[102:105]
	v_mfma_f32_16x16x32_bf16 v[98:101], v[174:177], v[190:193], v[98:101]
	v_mfma_f32_16x16x32_bf16 v[86:89], v[156:159], v[198:201], v[86:89]
	v_mfma_f32_16x16x32_bf16 v[82:85], v[174:177], v[198:201], v[82:85]
	v_mfma_f32_16x16x32_bf16 v[70:73], v[156:159], v[206:209], v[70:73]
	v_mfma_f32_16x16x32_bf16 v[66:69], v[174:177], v[206:209], v[66:69]
	v_mfma_f32_16x16x32_bf16 v[118:121], v[170:173], v[186:189], v[118:121]
	v_mfma_f32_16x16x32_bf16 v[114:117], v[178:181], v[186:189], v[114:117]
	v_mfma_f32_16x16x32_bf16 v[102:105], v[170:173], v[194:197], v[102:105]
	v_mfma_f32_16x16x32_bf16 v[98:101], v[178:181], v[194:197], v[98:101]
	v_mfma_f32_16x16x32_bf16 v[86:89], v[170:173], v[202:205], v[86:89]
	v_mfma_f32_16x16x32_bf16 v[82:85], v[178:181], v[202:205], v[82:85]
	v_mfma_f32_16x16x32_bf16 v[70:73], v[170:173], v[230:233], v[70:73]
	v_mfma_f32_16x16x32_bf16 v[66:69], v[178:181], v[230:233], v[66:69]
	s_setprio 1
	s_barrier
; #define PG8_STAGE(bufoff, gbase, voff) do { _Pragma("unroll") for (int _i = 0; _i < 2; ++_i) \
;         __builtin_amdgcn_global_load_lds((const unsigned*)((const char*)(gbase) + (voff)[_i]), (PG8_LAS unsigned*)(lds + (bufoff) + ldsw + _i * 8192), 16, 0, 0); } while (0)
; #define PG8_LDA(dst, b, h) do { _Pragma("unroll") for (int m = 0; m < 4; ++m) _Pragma("unroll") for (int k = 0; k < 2; ++k) dst[m][k] = *(const PG8_LAS bf16x8*)(lds + PG8_SA(b, h) + aoff + m * 2048 + k * 1024); } while (0)
; #define PG8_LDB(dst, b, h) do { _Pragma("unroll") for (int n = 0; n < 2; ++n) _Pragma("unroll") for (int k = 0; k < 2; ++k) dst[n][k] = *(const PG8_LAS bf16x8*)(lds + PG8_SB(b, h) + boff + n * 2048 + k * 1024); } while (0)
; #define PG8_MMA(ai, bj, At, Bt) do { __builtin_amdgcn_s_setprio(1); _Pragma("unroll") for (int m = 0; m < 4; ++m) _Pragma("unroll") for (int n = 0; n < 2; ++n) _Pragma("unroll") for (int k = 0; k < 2; ++k) \
;         acc[ai][bj][m][n] = __builtin_amdgcn_mfma_f32_16x16x32_bf16(Bt[n][k], At[m][k], acc[ai][bj][m][n], 0, 0, 0); __builtin_amdgcn_s_setprio(0); } while (0)
; #define PG8_WAIT_V(n) asm volatile("s_waitcnt vmcnt(" #n ")" ::: "memory")
; #define PG8_BAR __builtin_amdgcn_s_barrier()
; template <class Epi, class Sched, bool ALIGN_EPI = false, bool SP2 = false>
; __device__ __forceinline__ void gemm_phase(PG8_LAS unsigned char* lds, const Gemm g, const Sched& S, const Epi& E) {
;     ...
;         for (int t = 0; t < nt; t += 2) {
;             const bool last = (t == nt - 2);
;             const char* a1 = cA + (size_t)(t + 1) * kstep;
;             const char* a2 = last ? nA : cA + (size_t)(t + 2) * kstep; const char* b2 = last ? nB : cB + (size_t)(t + 2) * kstep;
;             const char* a3 = a2 + kstep; const char* b3 = b2 + kstep;
;             if (last && has_next) S.a_ready(nxt);
;             if constexpr (SP2) {
;             PG8_LDB(B0, 0, 0); PG8_LDB(B1, 0, 1); PG8_SCHED; PG8_LDA(At, 0, 0); PG8_STAGE(PG8_SA(1, 1), a1 + hstep, voffA);
;             PG8_WAIT_V(8); PG8_WAIT_L(0); PG8_BAR; PG8_MMA(0, 0, At, B0); PG8_MMA(0, 1, At, B1); PG8_BAR; PG8_SCHED;
;     ...
;             PG8_LDA(At, 1, 1); PG8_STAGE(PG8_SB(1, 0), b3, voffB); PG8_STAGE(PG8_SB(1, 1), b3 + hstep, voffB); PG8_STAGE(PG8_SA(1, 0), a3, voffA);
;             PG8_WAIT_V(8); PG8_WAIT_L(0); PG8_BAR; PG8_MMA(1, 0, At, B0); PG8_MMA(1, 1, At, B1); PG8_BAR; PG8_SCHED;
	s_add_i32 s16, s36, s65
	v_lshl_add_u64 v[210:211], v[210:211], 0, s[44:45]
	s_mov_b32 m0, s16
	ds_read_b128 v[182:185], v169 offset:49152
	ds_read_b128 v[186:189], v169 offset:50176
	ds_read_b128 v[190:193], v169 offset:51200
	ds_read_b128 v[194:197], v169 offset:52224
	ds_read_b128 v[198:201], v169 offset:53248
	ds_read_b128 v[202:205], v169 offset:54272
	ds_read_b128 v[206:209], v169 offset:55296
	ds_read_b128 v[230:233], v169 offset:56320
	global_load_lds_dwordx4 v[210:211], off
	v_lshl_add_u64 v[210:211], v[234:235], 0, s[44:45]
	s_add_i32 m0, s16, 0x2000
	s_add_i32 s16, s41, s65
	global_load_lds_dwordx4 v[210:211], off
	v_lshl_add_u64 v[210:211], v[236:237], 0, s[44:45]
	s_mov_b32 m0, s16
	s_nop 0
	global_load_lds_dwordx4 v[210:211], off
	v_lshl_add_u64 v[210:211], v[238:239], 0, s[44:45]
	s_add_i32 m0, s16, 0x2000
	s_nop 0
	global_load_lds_dwordx4 v[210:211], off
	v_lshl_add_u64 v[210:211], v[244:245], 0, s[44:45]
	s_mov_b32 m0, s73
	s_nop 0
	global_load_lds_dwordx4 v[210:211], off
	v_lshl_add_u64 v[210:211], v[246:247], 0, s[44:45]
	s_mov_b32 m0, s68
	s_nop 0
	global_load_lds_dwordx4 v[210:211], off
	s_waitcnt vmcnt(8)
	s_waitcnt lgkmcnt(0)
	s_barrier
	s_setprio 0
	s_waitcnt lgkmcnt(0)
	v_mfma_f32_16x16x32_bf16 v[60:63], v[140:143], v[182:185], v[60:63]
	v_mfma_f32_16x16x32_bf16 v[56:59], v[148:151], v[182:185], v[56:59]
	v_mfma_f32_16x16x32_bf16 v[44:47], v[140:143], v[190:193], v[44:47]
	v_mfma_f32_16x16x32_bf16 v[40:43], v[148:151], v[190:193], v[40:43]
	v_mfma_f32_16x16x32_bf16 v[28:31], v[140:143], v[198:201], v[28:31]
	v_mfma_f32_16x16x32_bf16 v[24:27], v[148:151], v[198:201], v[24:27]
	v_mfma_f32_16x16x32_bf16 v[12:15], v[140:143], v[206:209], v[12:15]
	v_mfma_f32_16x16x32_bf16 v[8:11], v[148:151], v[206:209], v[8:11]
	v_mfma_f32_16x16x32_bf16 v[60:63], v[144:147], v[186:189], v[60:63]
	v_mfma_f32_16x16x32_bf16 v[56:59], v[152:155], v[186:189], v[56:59]
	v_mfma_f32_16x16x32_bf16 v[44:47], v[144:147], v[194:197], v[44:47]
	v_mfma_f32_16x16x32_bf16 v[40:43], v[152:155], v[194:197], v[40:43]
	v_mfma_f32_16x16x32_bf16 v[28:31], v[144:147], v[202:205], v[28:31]
	v_mfma_f32_16x16x32_bf16 v[24:27], v[152:155], v[202:205], v[24:27]
	v_mfma_f32_16x16x32_bf16 v[12:15], v[144:147], v[230:233], v[12:15]
	v_mfma_f32_16x16x32_bf16 v[8:11], v[152:155], v[230:233], v[8:11]
	s_setprio 1
	s_setprio 0
	v_mfma_f32_16x16x32_bf16 v[52:55], v[156:159], v[182:185], v[52:55]
	v_mfma_f32_16x16x32_bf16 v[48:51], v[174:177], v[182:185], v[48:51]
	v_mfma_f32_16x16x32_bf16 v[36:39], v[156:159], v[190:193], v[36:39]
	v_mfma_f32_16x16x32_bf16 v[32:35], v[174:177], v[190:193], v[32:35]
	v_mfma_f32_16x16x32_bf16 v[20:23], v[156:159], v[198:201], v[20:23]
	v_mfma_f32_16x16x32_bf16 v[16:19], v[174:177], v[198:201], v[16:19]
	v_mfma_f32_16x16x32_bf16 v[4:7], v[156:159], v[206:209], v[4:7]
	v_mfma_f32_16x16x32_bf16 v[0:3], v[174:177], v[206:209], v[0:3]
	v_mfma_f32_16x16x32_bf16 v[52:55], v[170:173], v[186:189], v[52:55]
	v_mfma_f32_16x16x32_bf16 v[48:51], v[178:181], v[186:189], v[48:51]
	v_mfma_f32_16x16x32_bf16 v[36:39], v[170:173], v[194:197], v[36:39]
	v_mfma_f32_16x16x32_bf16 v[32:35], v[178:181], v[194:197], v[32:35]
	v_mfma_f32_16x16x32_bf16 v[20:23], v[170:173], v[202:205], v[20:23]
	v_mfma_f32_16x16x32_bf16 v[16:19], v[178:181], v[202:205], v[16:19]
	v_mfma_f32_16x16x32_bf16 v[4:7], v[170:173], v[230:233], v[4:7]
	v_mfma_f32_16x16x32_bf16 v[0:3], v[178:181], v[230:233], v[0:3]
	s_setprio 1
	s_barrier
	s_add_u32 s8, s8, 0x100
	s_addc_u32 s9, s9, 0
	s_add_u32 s27, s27, 0x100
	s_addc_u32 s30, s30, 0
	s_cmp_ge_u32 s31, s87
	s_mov_b32 s16, s31
	s_cbranch_scc0 .LBB0_688
	s_branch .Lk_loop_done
.LBB0_688:
	s_add_i32 s31, s16, 2
	s_add_u32 s36, s8, 0x80
	s_addc_u32 s17, s9, 0
	s_add_i32 s41, 0, 0x10000
	s_cmp_eq_u32 s72, s16
	s_cselect_b32 s17, s1, s17
	s_cselect_b32 s16, s0, s36
	s_cselect_b32 vcc_hi, s93, s30
	s_cselect_b32 vcc_lo, s92, s27
	s_add_i32 s36, 0, 0x14000
	v_add_u32_e32 v152, s41, v161
	v_add_u32_e32 v178, s36, v161
	ds_read_b128 v[140:143], v152
	ds_read_b128 v[144:147], v152 offset:1024
	ds_read_b128 v[148:151], v152 offset:2048
	ds_read_b128 v[152:155], v152 offset:3072
	ds_read_b128 v[156:159], v178
	ds_read_b128 v[170:173], v178 offset:1024
	ds_read_b128 v[174:177], v178 offset:2048
	ds_read_b128 v[178:181], v178 offset:3072
	v_lshl_add_u64 v[210:211], s[8:9], 0, v[136:137]
	s_add_i32 m0, s76, 0xc000
	ds_read_b128 v[182:185], v169
	ds_read_b128 v[186:189], v169 offset:1024
	ds_read_b128 v[190:193], v169 offset:2048
	ds_read_b128 v[194:197], v169 offset:3072
	ds_read_b128 v[198:201], v169 offset:4096
	ds_read_b128 v[202:205], v169 offset:5120
	ds_read_b128 v[206:209], v169 offset:6144
	ds_read_b128 v[230:233], v169 offset:7168
	global_load_lds_dwordx4 v[210:211], off
	v_lshl_add_u64 v[210:211], s[8:9], 0, v[138:139]
	s_add_i32 m0, s76, 0xe000
	s_nop 0
	global_load_lds_dwordx4 v[210:211], off
	s_waitcnt vmcnt(8)
	s_waitcnt lgkmcnt(0)
	s_barrier
; #define PG8_STAGE(bufoff, gbase, voff) do { _Pragma("unroll") for (int _i = 0; _i < 2; ++_i) \
;         __builtin_amdgcn_global_load_lds((const unsigned*)((const char*)(gbase) + (voff)[_i]), (PG8_LAS unsigned*)(lds + (bufoff) + ldsw + _i * 8192), 16, 0, 0); } while (0)
; #define PG8_LDA(dst, b, h) do { _Pragma("unroll") for (int m = 0; m < 4; ++m) _Pragma("unroll") for (int k = 0; k < 2; ++k) dst[m][k] = *(const PG8_LAS bf16x8*)(lds + PG8_SA(b, h) + aoff + m * 2048 + k * 1024); } while (0)
; #define PG8_LDB(dst, b, h) do { _Pragma("unroll") for (int n = 0; n < 2; ++n) _Pragma("unroll") for (int k = 0; k < 2; ++k) dst[n][k] = *(const PG8_LAS bf16x8*)(lds + PG8_SB(b, h) + boff + n * 2048 + k * 1024); } while (0)
; #define PG8_MMA(ai, bj, At, Bt) do { __builtin_amdgcn_s_setprio(1); _Pragma("unroll") for (int m = 0; m < 4; ++m) _Pragma("unroll") for (int n = 0; n < 2; ++n) _Pragma("unroll") for (int k = 0; k < 2; ++k) \
;         acc[ai][bj][m][n] = __builtin_amdgcn_mfma_f32_16x16x32_bf16(Bt[n][k], At[m][k], acc[ai][bj][m][n], 0, 0, 0); __builtin_amdgcn_s_setprio(0); } while (0)
; #define PG8_WAIT_V(n) asm volatile("s_waitcnt vmcnt(" #n ")" ::: "memory")
; #define PG8_WAIT_L(n) asm volatile("s_waitcnt lgkmcnt(" #n ")" ::: "memory")
; #define PG8_BAR __builtin_amdgcn_s_barrier()
; #define PG8_SCHED __builtin_amdgcn_sched_barrier(0)
; template <class Epi, class Sched, bool ALIGN_EPI = false, bool SP2 = false>
; __device__ __forceinline__ void gemm_phase(PG8_LAS unsigned char* lds, const Gemm g, const Sched& S, const Epi& E) {
;     ...
;             PG8_LDB(B0, 0, 0); PG8_LDB(B1, 0, 1); PG8_SCHED; PG8_LDA(At, 0, 0); PG8_STAGE(PG8_SA(1, 1), a1 + hstep, voffA);
;             PG8_WAIT_V(8); PG8_WAIT_L(0); PG8_BAR; PG8_MMA(0, 0, At, B0); PG8_MMA(0, 1, At, B1); PG8_BAR; PG8_SCHED;
;             PG8_LDA(At, 0, 1); PG8_STAGE(PG8_SB(0, 0), b2, voffB); PG8_STAGE(PG8_SB(0, 1), b2 + hstep, voffB); PG8_STAGE(PG8_SA(0, 0), a2, voffA);
;             PG8_WAIT_V(8); PG8_WAIT_L(0); PG8_BAR; PG8_MMA(1, 0, At, B0); PG8_MMA(1, 1, At, B1); PG8_BAR; PG8_SCHED;
;             PG8_LDB(B0, 1, 0); PG8_LDB(B1, 1, 1); PG8_SCHED; PG8_LDA(At, 1, 0); PG8_STAGE(PG8_SA(0, 1), a2 + hstep, voffA);
	s_setprio 0
	s_waitcnt lgkmcnt(0)
	v_mfma_f32_16x16x32_bf16 v[126:129], v[140:143], v[182:185], v[126:129]
	v_mfma_f32_16x16x32_bf16 v[122:125], v[148:151], v[182:185], v[122:125]
	v_mfma_f32_16x16x32_bf16 v[110:113], v[140:143], v[190:193], v[110:113]
	v_mfma_f32_16x16x32_bf16 v[106:109], v[148:151], v[190:193], v[106:109]
	v_mfma_f32_16x16x32_bf16 v[94:97], v[140:143], v[198:201], v[94:97]
	v_mfma_f32_16x16x32_bf16 v[90:93], v[148:151], v[198:201], v[90:93]
	v_mfma_f32_16x16x32_bf16 v[78:81], v[140:143], v[206:209], v[78:81]
	v_mfma_f32_16x16x32_bf16 v[74:77], v[148:151], v[206:209], v[74:77]
	v_mfma_f32_16x16x32_bf16 v[126:129], v[144:147], v[186:189], v[126:129]
	v_mfma_f32_16x16x32_bf16 v[122:125], v[152:155], v[186:189], v[122:125]
	v_mfma_f32_16x16x32_bf16 v[110:113], v[144:147], v[194:197], v[110:113]
	v_mfma_f32_16x16x32_bf16 v[106:109], v[152:155], v[194:197], v[106:109]
	v_mfma_f32_16x16x32_bf16 v[94:97], v[144:147], v[202:205], v[94:97]
	v_mfma_f32_16x16x32_bf16 v[90:93], v[152:155], v[202:205], v[90:93]
	v_mfma_f32_16x16x32_bf16 v[78:81], v[144:147], v[230:233], v[78:81]
	v_mfma_f32_16x16x32_bf16 v[74:77], v[152:155], v[230:233], v[74:77]
	s_setprio 1
	s_setprio 0
	v_mfma_f32_16x16x32_bf16 v[118:121], v[156:159], v[182:185], v[118:121]
	v_mfma_f32_16x16x32_bf16 v[114:117], v[174:177], v[182:185], v[114:117]
	v_mfma_f32_16x16x32_bf16 v[102:105], v[156:159], v[190:193], v[102:105]
	v_mfma_f32_16x16x32_bf16 v[98:101], v[174:177], v[190:193], v[98:101]
	v_mfma_f32_16x16x32_bf16 v[86:89], v[156:159], v[198:201], v[86:89]
	v_mfma_f32_16x16x32_bf16 v[82:85], v[174:177], v[198:201], v[82:85]
	v_mfma_f32_16x16x32_bf16 v[70:73], v[156:159], v[206:209], v[70:73]
	v_mfma_f32_16x16x32_bf16 v[66:69], v[174:177], v[206:209], v[66:69]
	v_mfma_f32_16x16x32_bf16 v[118:121], v[170:173], v[186:189], v[118:121]
	v_mfma_f32_16x16x32_bf16 v[114:117], v[178:181], v[186:189], v[114:117]
	v_mfma_f32_16x16x32_bf16 v[102:105], v[170:173], v[194:197], v[102:105]
	v_mfma_f32_16x16x32_bf16 v[98:101], v[178:181], v[194:197], v[98:101]
	v_mfma_f32_16x16x32_bf16 v[86:89], v[170:173], v[202:205], v[86:89]
	v_mfma_f32_16x16x32_bf16 v[82:85], v[178:181], v[202:205], v[82:85]
	v_mfma_f32_16x16x32_bf16 v[70:73], v[170:173], v[230:233], v[70:73]
	v_mfma_f32_16x16x32_bf16 v[66:69], v[178:181], v[230:233], v[66:69]
	s_setprio 1
	s_barrier
	s_add_i32 s41, s41, s65
	v_lshl_add_u64 v[210:211], vcc, 0, v[64:65]
	s_mov_b32 m0, s41
	ds_read_b128 v[182:185], v169 offset:16384
	ds_read_b128 v[186:189], v169 offset:17408
	ds_read_b128 v[190:193], v169 offset:18432
	ds_read_b128 v[194:197], v169 offset:19456
	ds_read_b128 v[198:201], v169 offset:20480
	ds_read_b128 v[202:205], v169 offset:21504
	ds_read_b128 v[206:209], v169 offset:22528
	ds_read_b128 v[230:233], v169 offset:23552
	global_load_lds_dwordx4 v[210:211], off
	s_add_i32 m0, s41, 0x2000
	v_lshl_add_u64 v[234:235], vcc, 0, v[134:135]
	s_add_u32 vcc_lo, vcc_lo, s4
	s_addc_u32 vcc_hi, vcc_hi, 0
	s_add_i32 s36, s36, s65
	global_load_lds_dwordx4 v[234:235], off
	v_lshl_add_u64 v[236:237], vcc, 0, v[64:65]
	s_mov_b32 m0, s36
	v_lshl_add_u64 v[238:239], vcc, 0, v[134:135]
	global_load_lds_dwordx4 v[236:237], off
	s_add_i32 m0, s36, 0x2000
	v_lshl_add_u64 v[244:245], s[16:17], 0, v[130:131]
	global_load_lds_dwordx4 v[238:239], off
	s_mov_b32 m0, s76
	v_lshl_add_u64 v[246:247], s[16:17], 0, v[132:133]
	global_load_lds_dwordx4 v[244:245], off
	s_mov_b32 m0, s2
	s_nop 0
	global_load_lds_dwordx4 v[246:247], off
	s_waitcnt vmcnt(8)
	s_waitcnt lgkmcnt(0)
	s_barrier
	s_setprio 0
	s_waitcnt lgkmcnt(0)
	v_mfma_f32_16x16x32_bf16 v[60:63], v[140:143], v[182:185], v[60:63]
	v_mfma_f32_16x16x32_bf16 v[56:59], v[148:151], v[182:185], v[56:59]
	v_mfma_f32_16x16x32_bf16 v[44:47], v[140:143], v[190:193], v[44:47]
	v_mfma_f32_16x16x32_bf16 v[40:43], v[148:151], v[190:193], v[40:43]
	v_mfma_f32_16x16x32_bf16 v[28:31], v[140:143], v[198:201], v[28:31]
	v_mfma_f32_16x16x32_bf16 v[24:27], v[148:151], v[198:201], v[24:27]
	v_mfma_f32_16x16x32_bf16 v[12:15], v[140:143], v[206:209], v[12:15]
	v_mfma_f32_16x16x32_bf16 v[8:11], v[148:151], v[206:209], v[8:11]
	v_mfma_f32_16x16x32_bf16 v[60:63], v[144:147], v[186:189], v[60:63]
	v_mfma_f32_16x16x32_bf16 v[56:59], v[152:155], v[186:189], v[56:59]
	v_mfma_f32_16x16x32_bf16 v[44:47], v[144:147], v[194:197], v[44:47]
	v_mfma_f32_16x16x32_bf16 v[40:43], v[152:155], v[194:197], v[40:43]
	v_mfma_f32_16x16x32_bf16 v[28:31], v[144:147], v[202:205], v[28:31]
	v_mfma_f32_16x16x32_bf16 v[24:27], v[152:155], v[202:205], v[24:27]
	v_mfma_f32_16x16x32_bf16 v[12:15], v[144:147], v[230:233], v[12:15]
	v_mfma_f32_16x16x32_bf16 v[8:11], v[152:155], v[230:233], v[8:11]
	s_setprio 1
	s_setprio 0
	v_mfma_f32_16x16x32_bf16 v[52:55], v[156:159], v[182:185], v[52:55]
	v_mfma_f32_16x16x32_bf16 v[48:51], v[174:177], v[182:185], v[48:51]
	v_mfma_f32_16x16x32_bf16 v[36:39], v[156:159], v[190:193], v[36:39]
	v_mfma_f32_16x16x32_bf16 v[32:35], v[174:177], v[190:193], v[32:35]
	v_mfma_f32_16x16x32_bf16 v[20:23], v[156:159], v[198:201], v[20:23]
	v_mfma_f32_16x16x32_bf16 v[16:19], v[174:177], v[198:201], v[16:19]
	v_mfma_f32_16x16x32_bf16 v[4:7], v[156:159], v[206:209], v[4:7]
	v_mfma_f32_16x16x32_bf16 v[0:3], v[174:177], v[206:209], v[0:3]
	v_mfma_f32_16x16x32_bf16 v[52:55], v[170:173], v[186:189], v[52:55]
	v_mfma_f32_16x16x32_bf16 v[48:51], v[178:181], v[186:189], v[48:51]
	v_mfma_f32_16x16x32_bf16 v[36:39], v[170:173], v[194:197], v[36:39]
	v_mfma_f32_16x16x32_bf16 v[32:35], v[178:181], v[194:197], v[32:35]
	v_mfma_f32_16x16x32_bf16 v[20:23], v[170:173], v[202:205], v[20:23]
	v_mfma_f32_16x16x32_bf16 v[16:19], v[178:181], v[202:205], v[16:19]
	v_mfma_f32_16x16x32_bf16 v[4:7], v[170:173], v[230:233], v[4:7]
	v_mfma_f32_16x16x32_bf16 v[0:3], v[178:181], v[230:233], v[0:3]
	s_setprio 1
	s_barrier
; #define PG8_STAGE(bufoff, gbase, voff) do { _Pragma("unroll") for (int _i = 0; _i < 2; ++_i) \
;         __builtin_amdgcn_global_load_lds((const unsigned*)((const char*)(gbase) + (voff)[_i]), (PG8_LAS unsigned*)(lds + (bufoff) + ldsw + _i * 8192), 16, 0, 0); } while (0)
; #define PG8_LDA(dst, b, h) do { _Pragma("unroll") for (int m = 0; m < 4; ++m) _Pragma("unroll") for (int k = 0; k < 2; ++k) dst[m][k] = *(const PG8_LAS bf16x8*)(lds + PG8_SA(b, h) + aoff + m * 2048 + k * 1024); } while (0)
; #define PG8_LDB(dst, b, h) do { _Pragma("unroll") for (int n = 0; n < 2; ++n) _Pragma("unroll") for (int k = 0; k < 2; ++k) dst[n][k] = *(const PG8_LAS bf16x8*)(lds + PG8_SB(b, h) + boff + n * 2048 + k * 1024); } while (0)
; #define PG8_MMA(ai, bj, At, Bt) do { __builtin_amdgcn_s_setprio(1); _Pragma("unroll") for (int m = 0; m < 4; ++m) _Pragma("unroll") for (int n = 0; n < 2; ++n) _Pragma("unroll") for (int k = 0; k < 2; ++k) \
;         acc[ai][bj][m][n] = __builtin_amdgcn_mfma_f32_16x16x32_bf16(Bt[n][k], At[m][k], acc[ai][bj][m][n], 0, 0, 0); __builtin_amdgcn_s_setprio(0); } while (0)
; #define PG8_WAIT_V(n) asm volatile("s_waitcnt vmcnt(" #n ")" ::: "memory")
; #define PG8_WAIT_L(n) asm volatile("s_waitcnt lgkmcnt(" #n ")" ::: "memory")
; #define PG8_BAR __builtin_amdgcn_s_barrier()
; #define PG8_SCHED __builtin_amdgcn_sched_barrier(0)
; template <class Epi, class Sched, bool ALIGN_EPI = false, bool SP2 = false>
; __device__ __forceinline__ void gemm_phase(PG8_LAS unsigned char* lds, const Gemm g, const Sched& S, const Epi& E) {
;     ...
;             PG8_LDB(B0, 1, 0); PG8_LDB(B1, 1, 1); PG8_SCHED; PG8_LDA(At, 1, 0); PG8_STAGE(PG8_SA(0, 1), a2 + hstep, voffA);
;             PG8_WAIT_V(8); PG8_WAIT_L(0); PG8_BAR; PG8_MMA(0, 0, At, B0); PG8_MMA(0, 1, At, B1); PG8_BAR; PG8_SCHED;
	s_add_i32 s36, 0, 0x18000
	s_add_i32 s41, 0, 0x1c000
	v_add_u32_e32 v152, s36, v161
	v_add_u32_e32 v178, s41, v161
	ds_read_b128 v[140:143], v152
	ds_read_b128 v[144:147], v152 offset:1024
	ds_read_b128 v[148:151], v152 offset:2048
	ds_read_b128 v[152:155], v152 offset:3072
	ds_read_b128 v[156:159], v178
	ds_read_b128 v[170:173], v178 offset:1024
	ds_read_b128 v[174:177], v178 offset:2048
	ds_read_b128 v[178:181], v178 offset:3072
	s_add_u32 s16, s16, s4
	s_addc_u32 s17, s17, 0
	s_mov_b32 m0, s3
	v_lshl_add_u64 v[248:249], s[16:17], 0, v[130:131]
	ds_read_b128 v[182:185], v169 offset:32768
	ds_read_b128 v[186:189], v169 offset:33792
	ds_read_b128 v[190:193], v169 offset:34816
	ds_read_b128 v[194:197], v169 offset:35840
	ds_read_b128 v[198:201], v169 offset:36864
	ds_read_b128 v[202:205], v169 offset:37888
	ds_read_b128 v[206:209], v169 offset:38912
	ds_read_b128 v[230:233], v169 offset:39936
	global_load_lds_dwordx4 v[248:249], off
	v_lshl_add_u64 v[248:249], s[16:17], 0, v[132:133]
	s_mov_b32 m0, s70
	s_nop 0
	global_load_lds_dwordx4 v[248:249], off
	s_waitcnt vmcnt(8)
	s_waitcnt lgkmcnt(0)
	s_barrier
	s_setprio 0
	s_waitcnt lgkmcnt(0)
	v_mfma_f32_16x16x32_bf16 v[126:129], v[140:143], v[182:185], v[126:129]
	v_mfma_f32_16x16x32_bf16 v[122:125], v[148:151], v[182:185], v[122:125]
	v_mfma_f32_16x16x32_bf16 v[110:113], v[140:143], v[190:193], v[110:113]
	v_mfma_f32_16x16x32_bf16 v[106:109], v[148:151], v[190:193], v[106:109]
	v_mfma_f32_16x16x32_bf16 v[94:97], v[140:143], v[198:201], v[94:97]
	v_mfma_f32_16x16x32_bf16 v[90:93], v[148:151], v[198:201], v[90:93]
	v_mfma_f32_16x16x32_bf16 v[78:81], v[140:143], v[206:209], v[78:81]
	v_mfma_f32_16x16x32_bf16 v[74:77], v[148:151], v[206:209], v[74:77]
	v_mfma_f32_16x16x32_bf16 v[126:129], v[144:147], v[186:189], v[126:129]
	v_mfma_f32_16x16x32_bf16 v[122:125], v[152:155], v[186:189], v[122:125]
	v_mfma_f32_16x16x32_bf16 v[110:113], v[144:147], v[194:197], v[110:113]
	v_mfma_f32_16x16x32_bf16 v[106:109], v[152:155], v[194:197], v[106:109]
	v_mfma_f32_16x16x32_bf16 v[94:97], v[144:147], v[202:205], v[94:97]
	v_mfma_f32_16x16x32_bf16 v[90:93], v[152:155], v[202:205], v[90:93]
	v_mfma_f32_16x16x32_bf16 v[78:81], v[144:147], v[230:233], v[78:81]
	v_mfma_f32_16x16x32_bf16 v[74:77], v[152:155], v[230:233], v[74:77]
	s_setprio 1
	s_setprio 0
	v_mfma_f32_16x16x32_bf16 v[118:121], v[156:159], v[182:185], v[118:121]
	v_mfma_f32_16x16x32_bf16 v[114:117], v[174:177], v[182:185], v[114:117]
	v_mfma_f32_16x16x32_bf16 v[102:105], v[156:159], v[190:193], v[102:105]
	v_mfma_f32_16x16x32_bf16 v[98:101], v[174:177], v[190:193], v[98:101]
	v_mfma_f32_16x16x32_bf16 v[86:89], v[156:159], v[198:201], v[86:89]
	v_mfma_f32_16x16x32_bf16 v[82:85], v[174:177], v[198:201], v[82:85]
	v_mfma_f32_16x16x32_bf16 v[70:73], v[156:159], v[206:209], v[70:73]
	v_mfma_f32_16x16x32_bf16 v[66:69], v[174:177], v[206:209], v[66:69]
	v_mfma_f32_16x16x32_bf16 v[118:121], v[170:173], v[186:189], v[118:121]
	v_mfma_f32_16x16x32_bf16 v[114:117], v[178:181], v[186:189], v[114:117]
	v_mfma_f32_16x16x32_bf16 v[102:105], v[170:173], v[194:197], v[102:105]
	v_mfma_f32_16x16x32_bf16 v[98:101], v[178:181], v[194:197], v[98:101]
	v_mfma_f32_16x16x32_bf16 v[86:89], v[170:173], v[202:205], v[86:89]
	v_mfma_f32_16x16x32_bf16 v[82:85], v[178:181], v[202:205], v[82:85]
	v_mfma_f32_16x16x32_bf16 v[70:73], v[170:173], v[230:233], v[70:73]
	v_mfma_f32_16x16x32_bf16 v[66:69], v[178:181], v[230:233], v[66:69]
	s_setprio 1
	s_barrier
; #define PG8_STAGE(bufoff, gbase, voff) do { _Pragma("unroll") for (int _i = 0; _i < 2; ++_i) \
;         __builtin_amdgcn_global_load_lds((const unsigned*)((const char*)(gbase) + (voff)[_i]), (PG8_LAS unsigned*)(lds + (bufoff) + ldsw + _i * 8192), 16, 0, 0); } while (0)
; #define PG8_LDA(dst, b, h) do { _Pragma("unroll") for (int m = 0; m < 4; ++m) _Pragma("unroll") for (int k = 0; k < 2; ++k) dst[m][k] = *(const PG8_LAS bf16x8*)(lds + PG8_SA(b, h) + aoff + m * 2048 + k * 1024); } while (0)
; #define PG8_MMA(ai, bj, At, Bt) do { __builtin_amdgcn_s_setprio(1); _Pragma("unroll") for (int m = 0; m < 4; ++m) _Pragma("unroll") for (int n = 0; n < 2; ++n) _Pragma("unroll") for (int k = 0; k < 2; ++k) \
;         acc[ai][bj][m][n] = __builtin_amdgcn_mfma_f32_16x16x32_bf16(Bt[n][k], At[m][k], acc[ai][bj][m][n], 0, 0, 0); __builtin_amdgcn_s_setprio(0); } while (0)
; #define PG8_WAIT_V(n) asm volatile("s_waitcnt vmcnt(" #n ")" ::: "memory")
; #define PG8_WAIT_L(n) asm volatile("s_waitcnt lgkmcnt(" #n ")" ::: "memory")
; #define PG8_BAR __builtin_amdgcn_s_barrier()
; #define PG8_SCHED __builtin_amdgcn_sched_barrier(0)
; template <class Epi, class Sched, bool ALIGN_EPI = false, bool SP2 = false>
; __device__ __forceinline__ void gemm_phase(PG8_LAS unsigned char* lds, const Gemm g, const Sched& S, const Epi& E) {
;     ...
;         for (int t = 0; t < nt; t += 2) {
;             const bool last = (t == nt - 2);
;             const char* a1 = cA + (size_t)(t + 1) * kstep;
;             const char* a2 = last ? nA : cA + (size_t)(t + 2) * kstep; const char* b2 = last ? nB : cB + (size_t)(t + 2) * kstep;
;             const char* a3 = a2 + kstep; const char* b3 = b2 + kstep;
;     ...
;             PG8_LDA(At, 1, 1); PG8_STAGE(PG8_SB(1, 0), b3, voffB); PG8_STAGE(PG8_SB(1, 1), b3 + hstep, voffB); PG8_STAGE(PG8_SA(1, 0), a3, voffA);
;             PG8_WAIT_V(8); PG8_WAIT_L(0); PG8_BAR; PG8_MMA(1, 0, At, B0); PG8_MMA(1, 1, At, B1); PG8_BAR; PG8_SCHED;
	s_add_i32 s16, s36, s65
	v_lshl_add_u64 v[210:211], v[210:211], 0, s[44:45]
	s_mov_b32 m0, s16
	ds_read_b128 v[182:185], v169 offset:49152
	ds_read_b128 v[186:189], v169 offset:50176
	ds_read_b128 v[190:193], v169 offset:51200
	ds_read_b128 v[194:197], v169 offset:52224
	ds_read_b128 v[198:201], v169 offset:53248
	ds_read_b128 v[202:205], v169 offset:54272
	ds_read_b128 v[206:209], v169 offset:55296
	ds_read_b128 v[230:233], v169 offset:56320
	global_load_lds_dwordx4 v[210:211], off
	v_lshl_add_u64 v[210:211], v[234:235], 0, s[44:45]
	s_add_i32 m0, s16, 0x2000
	s_add_i32 s16, s41, s65
	global_load_lds_dwordx4 v[210:211], off
	v_lshl_add_u64 v[210:211], v[236:237], 0, s[44:45]
	s_mov_b32 m0, s16
	s_nop 0
	global_load_lds_dwordx4 v[210:211], off
	v_lshl_add_u64 v[210:211], v[238:239], 0, s[44:45]
	s_add_i32 m0, s16, 0x2000
	s_nop 0
	global_load_lds_dwordx4 v[210:211], off
	v_lshl_add_u64 v[210:211], v[244:245], 0, s[44:45]
	s_mov_b32 m0, s73
	s_nop 0
	global_load_lds_dwordx4 v[210:211], off
	v_lshl_add_u64 v[210:211], v[246:247], 0, s[44:45]
	s_mov_b32 m0, s68
	s_nop 0
	global_load_lds_dwordx4 v[210:211], off
	s_waitcnt vmcnt(8)
	s_waitcnt lgkmcnt(0)
	s_barrier
	s_setprio 0
	s_waitcnt lgkmcnt(0)
	v_mfma_f32_16x16x32_bf16 v[60:63], v[140:143], v[182:185], v[60:63]
	v_mfma_f32_16x16x32_bf16 v[56:59], v[148:151], v[182:185], v[56:59]
	v_mfma_f32_16x16x32_bf16 v[44:47], v[140:143], v[190:193], v[44:47]
	v_mfma_f32_16x16x32_bf16 v[40:43], v[148:151], v[190:193], v[40:43]
	v_mfma_f32_16x16x32_bf16 v[28:31], v[140:143], v[198:201], v[28:31]
	v_mfma_f32_16x16x32_bf16 v[24:27], v[148:151], v[198:201], v[24:27]
	v_mfma_f32_16x16x32_bf16 v[12:15], v[140:143], v[206:209], v[12:15]
	v_mfma_f32_16x16x32_bf16 v[8:11], v[148:151], v[206:209], v[8:11]
	v_mfma_f32_16x16x32_bf16 v[60:63], v[144:147], v[186:189], v[60:63]
	v_mfma_f32_16x16x32_bf16 v[56:59], v[152:155], v[186:189], v[56:59]
	v_mfma_f32_16x16x32_bf16 v[44:47], v[144:147], v[194:197], v[44:47]
	v_mfma_f32_16x16x32_bf16 v[40:43], v[152:155], v[194:197], v[40:43]
	v_mfma_f32_16x16x32_bf16 v[28:31], v[144:147], v[202:205], v[28:31]
	v_mfma_f32_16x16x32_bf16 v[24:27], v[152:155], v[202:205], v[24:27]
	v_mfma_f32_16x16x32_bf16 v[12:15], v[144:147], v[230:233], v[12:15]
	v_mfma_f32_16x16x32_bf16 v[8:11], v[152:155], v[230:233], v[8:11]
	s_setprio 1
	s_setprio 0
	v_mfma_f32_16x16x32_bf16 v[52:55], v[156:159], v[182:185], v[52:55]
	v_mfma_f32_16x16x32_bf16 v[48:51], v[174:177], v[182:185], v[48:51]
	v_mfma_f32_16x16x32_bf16 v[36:39], v[156:159], v[190:193], v[36:39]
	v_mfma_f32_16x16x32_bf16 v[32:35], v[174:177], v[190:193], v[32:35]
	v_mfma_f32_16x16x32_bf16 v[20:23], v[156:159], v[198:201], v[20:23]
	v_mfma_f32_16x16x32_bf16 v[16:19], v[174:177], v[198:201], v[16:19]
	v_mfma_f32_16x16x32_bf16 v[4:7], v[156:159], v[206:209], v[4:7]
	v_mfma_f32_16x16x32_bf16 v[0:3], v[174:177], v[206:209], v[0:3]
	v_mfma_f32_16x16x32_bf16 v[52:55], v[170:173], v[186:189], v[52:55]
	v_mfma_f32_16x16x32_bf16 v[48:51], v[178:181], v[186:189], v[48:51]
	v_mfma_f32_16x16x32_bf16 v[36:39], v[170:173], v[194:197], v[36:39]
	v_mfma_f32_16x16x32_bf16 v[32:35], v[178:181], v[194:197], v[32:35]
	v_mfma_f32_16x16x32_bf16 v[20:23], v[170:173], v[202:205], v[20:23]
	v_mfma_f32_16x16x32_bf16 v[16:19], v[178:181], v[202:205], v[16:19]
	v_mfma_f32_16x16x32_bf16 v[4:7], v[170:173], v[230:233], v[4:7]
	v_mfma_f32_16x16x32_bf16 v[0:3], v[178:181], v[230:233], v[0:3]
	s_setprio 1
	s_barrier
	s_add_u32 s8, s8, 0x100
	s_addc_u32 s9, s9, 0
	s_add_u32 s27, s27, 0x100
	s_addc_u32 s30, s30, 0
	s_cmp_ge_u32 s31, s87
	s_mov_b32 s16, s31
	s_cbranch_scc0 .LBB0_688
